# MX: transposing LDS reads address 8 consecutive rows per 32-lane group (+V image pitch 160 B): bank-conflict-free K/V tr-reads
# speedup vs baseline: 1.0311x; 1.0022x over previous
; #define LAS __attribute__((address_space(3)))
; DI unsigned xb_ld(unsigned* p)              { return __hip_atomic_load(p, __ATOMIC_RELAXED, __HIP_MEMORY_SCOPE_AGENT); }
; DI unsigned xb_add(unsigned* p, unsigned v) { return __hip_atomic_fetch_add(p, v, __ATOMIC_RELAXED, __HIP_MEMORY_SCOPE_AGENT); }
; DI unsigned xb_xcc_id() { return (unsigned)__builtin_amdgcn_s_getreg((3 << 11) | 20) & 0xFu; }
; #define RUN(...) RUNR(1, __VA_ARGS__)
; __global__ void __launch_bounds__(NT, 2) fwd_megakernel(Params p) {
;     ...
;     const int G = gridDim.x, bid = blockIdx.x;
;     const int lo = p.ph_lo;
;     const bool fuse_pf = (G == 256) && (p.ph_lo == 0) && (p.ph_hi == N_PHASES);
;     const int hi = fuse_pf ? p.ph_hi - 1 : p.ph_hi;
;     int ph = 0, nsync = 0;
;     volatile LAS unsigned* xst = (volatile LAS unsigned*)(lds + LDS_BYTES - 16);
;     if (threadIdx.x < 4) xst[threadIdx.x] = 0u;
;     __syncthreads();
;     XcdBarrier xbar = xcd_barrier_post((unsigned*)(p.ws + WS_BAR), xst);
;     unsigned* slotw = (unsigned*)(p.ws + WS_BAR) + XCD_BAR_WORDS;
;     if (threadIdx.x == 0) { const unsigned xc = xb_xcc_id() & 7u; xst[2] = xc; xst[3] = xb_add(&slotw[64 * xc], 1u); }
;     ...
;     RUNR(REP_P0, phase0(p, lds, G, bid));
;     int vb = bid, vc = bid;
;     if (G == 256 && lo == 0 && hi > 1) {
;         bool ok = true;
;         for (int j = 0; j < 8; ++j) ok = ok && (xb_ld(&slotw[64 * j]) == 32u);
;         if (ok) { const int xc = (int)xst[2], sl = (int)xst[3]; vb = xc * 32 + sl; vc = sl * 8 + xc; }
;     }
;     vb = __builtin_amdgcn_readfirstlane(vb); vc = __builtin_amdgcn_readfirstlane(vc);
;     for (int l = 0; l < 2; ++l) {
;         const float* xin = (l == 0) ? p.x : p.out;
;         RUNR(REP_PN, phase_norm(p, l, xin, lds, G, bid));
;         for (int seg = 0; seg < NSEG; ++seg) {
;             RUNR(REP_G1, { phase_tables(p, l, seg, G, bid); pg8::Gemm g{(const bf16_t*)(p.ws + WS_H), (const bf16_t*)(p.ws + WS_WIN) + (size_t)l * NPC * D, D, D, MSEG / 256, NPC / 256, seg, 0};
;                   pg8::EpiP E{(bf16_t*)(p.ws + WS_P), p.pos, (const float*)(p.ws + WS_INVF), seg};
;                   pg8::gemm_phase(lds, g, G, vc, E); });
;             RUNR(REP_PE, phase_prep(p, l, seg, lds, G, bid));
;             RUN(phase_ps(p, seg, lds, G, bid));
;             RUNR(REP_MX, phase_mixer(p, seg, lds, G, vb));
.LBB0_118:
	s_lshl_b32 s8, s53, 3
	s_lshl_b32 s10, s94, 3
	s_add_u32 s0, s92, 0x100000
	v_writelane_b32 v252, s0, 12
	s_addc_u32 s0, s93, 0
	v_writelane_b32 v252, s0, 13
	s_add_u32 s0, s92, 0x180000
	v_writelane_b32 v252, s0, 14
	s_addc_u32 s0, s93, 0
	v_writelane_b32 v252, s0, 15
	s_add_u32 s0, s92, 0x4000000
	v_writelane_b32 v252, s0, 16
	s_addc_u32 s0, s93, 0
	v_writelane_b32 v252, s0, 17
	s_add_u32 s0, s92, 0x200000
	s_addc_u32 s1, s93, 0
	v_writelane_b32 v252, s0, 18
	v_readfirstlane_b32 s9, v2
	s_waitcnt lgkmcnt(0)
	s_movk_i32 s79, 0x3ff
	v_writelane_b32 v252, s1, 19
	s_mov_b32 s27, 0
	v_readlane_b32 s0, v252, 4
	v_readlane_b32 s1, v252, 5
	s_cmp_gt_i32 s0, -1
	s_cselect_b64 s[0:1], -1, 0
	v_writelane_b32 v252, s0, 20
	v_mbcnt_lo_u32_b32 v2, -1, 0
	s_mov_b32 s95, s9
	v_writelane_b32 v252, s1, 21
	s_add_u32 s0, s92, 0x200
	s_addc_u32 s1, s93, 0
	v_writelane_b32 v252, s0, 22
	v_mov_b32_e32 v204, 0x358637bd
	v_mov_b32_e32 v205, 0x260
	v_writelane_b32 v252, s1, 23
	s_add_u32 s0, s92, 0x1000
	s_addc_u32 s1, s93, 0
	v_writelane_b32 v252, s0, 24
	v_mov_b32_e32 v206, 1
	v_mov_b32_e32 v207, 0x3ecc95a3
	v_writelane_b32 v252, s1, 25
	s_add_u32 s0, s92, 0x1100
	s_addc_u32 s1, s93, 0
	v_writelane_b32 v252, s0, 26
	v_mov_b32_e32 v208, 0x480000
	v_mbcnt_hi_u32_b32 v203, -1, v2
	v_writelane_b32 v252, s1, 27
	s_add_u32 s0, s92, 0x1200
	s_addc_u32 s1, s93, 0
	v_writelane_b32 v252, s0, 28
	v_mov_b32_e32 v209, 0x7f800000
	v_mov_b32_e32 v162, 0x3f317218
	v_writelane_b32 v252, s1, 29
	s_add_u32 s0, s92, 0x1300
	s_addc_u32 s1, s93, 0
	v_writelane_b32 v252, s0, 30
	s_cmp_eq_u32 s26, 15
	v_mov_b64_e32 v[164:165], 0x900
	v_writelane_b32 v252, s1, 31
	s_cselect_b64 s[0:1], -1, 0
	v_writelane_b32 v252, s0, 32
	s_cmp_eq_u32 s26, 14
	v_mov_b64_e32 v[166:167], 0x8ff
	v_writelane_b32 v252, s1, 33
	s_cselect_b64 s[0:1], -1, 0
	v_writelane_b32 v252, s0, 34
	s_cmp_eq_u32 s26, 13
	v_mov_b32_e32 v210, 0x42800000
	v_writelane_b32 v252, s1, 35
	s_cselect_b64 s[0:1], -1, 0
	v_writelane_b32 v252, s0, 36
	s_cmp_eq_u32 s26, 12
	v_mov_b32_e32 v211, 0x42000000
	v_writelane_b32 v252, s1, 37
	s_cselect_b64 s[0:1], -1, 0
	v_writelane_b32 v252, s0, 38
	s_cmp_eq_u32 s26, 11
	v_not_b32_e32 v212, 63
	v_writelane_b32 v252, s1, 39
	s_cselect_b64 s[0:1], -1, 0
	v_writelane_b32 v252, s0, 40
	s_cmp_eq_u32 s26, 10
	v_mov_b32_e32 v213, 0x3d800000
	v_writelane_b32 v252, s1, 41
	s_cselect_b64 s[0:1], -1, 0
	v_writelane_b32 v252, s0, 42
	s_cmp_eq_u32 s26, 9
	v_mov_b32_e32 v214, 0x3f80
	v_writelane_b32 v252, s1, 43
	s_cselect_b64 s[0:1], -1, 0
	v_writelane_b32 v252, s0, 44
	s_cmp_eq_u32 s26, 8
	v_mov_b32_e32 v215, 0xc000
	v_writelane_b32 v252, s1, 45
	s_cselect_b64 s[0:1], -1, 0
	v_writelane_b32 v252, s0, 46
	s_cmp_eq_u32 s26, 7
	v_mov_b32_e32 v216, 0x2000
	v_writelane_b32 v252, s1, 47
	s_cselect_b64 s[0:1], -1, 0
	v_writelane_b32 v252, s0, 48
	s_cmp_eq_u32 s26, 6
	v_mov_b32_e32 v217, 0xc00
	v_writelane_b32 v252, s1, 49
	s_cselect_b64 s[0:1], -1, 0
	v_writelane_b32 v252, s0, 50
	s_cmp_eq_u32 s26, 5
	v_mov_b64_e32 v[168:169], 0x100
	v_writelane_b32 v252, s1, 51
	s_cselect_b64 s[0:1], -1, 0
	v_writelane_b32 v252, s0, 52
	s_cmp_eq_u32 s26, 4
	v_mov_b64_e32 v[170:171], 0xff
	v_writelane_b32 v252, s1, 53
	s_cselect_b64 s[0:1], -1, 0
	v_writelane_b32 v252, s0, 54
	s_cmp_eq_u32 s26, 3
	s_movk_i32 s82, 0x90
	v_writelane_b32 v252, s1, 55
	s_cselect_b64 s[0:1], -1, 0
	v_writelane_b32 v252, s0, 56
	s_cmp_eq_u32 s26, 2
	s_movk_i32 s96, 0x4800
	v_writelane_b32 v252, s1, 57
	s_cselect_b64 s[0:1], -1, 0
	v_writelane_b32 v252, s0, 58
	s_cmp_eq_u32 s26, 1
	s_movk_i32 s85, 0xdff
	v_writelane_b32 v252, s1, 59
	s_cselect_b64 s[0:1], -1, 0
	v_writelane_b32 v252, s0, 60
	s_cmp_eq_u32 s26, 0
	s_movk_i32 s89, 0x2000
	v_writelane_b32 v252, s1, 61
	s_cselect_b64 s[0:1], -1, 0
	v_writelane_b32 v252, s0, 62
	s_mov_b32 s39, 0x3fb8aa3b
	s_mov_b32 s16, 0xc2fc0000
	v_writelane_b32 v252, s1, 63
	s_lshl_b32 s0, s26, 8
	s_add_u32 s0, s92, s0
	s_addc_u32 s1, s93, 0
	s_add_u32 s2, s0, 0x1400
	s_addc_u32 s3, s1, 0
	v_writelane_b32 v251, s2, 0
	v_readlane_b32 s12, v252, 6
	v_readlane_b32 s13, v252, 7
	v_writelane_b32 v251, s3, 1
	s_add_u32 s2, s92, 0x3500
	s_addc_u32 s3, s93, 0
	v_writelane_b32 v251, s2, 2
	s_mov_b32 s26, s27
	s_mov_b32 s58, 0x42fc0000
	v_writelane_b32 v251, s3, 3
	s_add_u32 s2, s92, 0x3400
	s_addc_u32 s3, s93, 0
	s_add_u32 s0, s0, 0x2400
	v_writelane_b32 v251, s2, 4
	s_addc_u32 s1, s1, 0
	s_add_u32 s20, s92, 0x300000
	v_writelane_b32 v251, s3, 5
	v_writelane_b32 v251, s0, 6
	s_addc_u32 s21, s93, 0
	s_movk_i32 s34, 0x210
	v_writelane_b32 v251, s1, 7
	s_add_u32 s0, s92, 0x4c0000
	s_addc_u32 s1, s93, 0
	v_writelane_b32 v251, s0, 8
	s_movk_i32 s59, 0x2400
	s_movk_i32 s37, 0xa0
	v_writelane_b32 v251, s1, 9
	s_add_u32 s0, s92, 0x1000000
	v_writelane_b32 v251, s0, 10
	s_addc_u32 s0, s93, 0
	s_add_u32 s24, s92, 0xc000000
	s_addc_u32 s25, s93, 0
	v_writelane_b32 v251, s0, 11
	s_add_u32 s0, s92, 0x120000
	v_writelane_b32 v251, s0, 12
	s_addc_u32 s0, s93, 0
	v_writelane_b32 v251, s0, 13
	s_ashr_i32 s0, s9, 31
	s_cmpk_lt_i32 s9, 0x900
	s_cselect_b64 s[2:3], -1, 0
	s_mov_b32 s7, s0
	s_lshr_b32 s0, s0, 29
	s_add_i32 s0, s9, s0
	s_ashr_i32 s1, s0, 3
	s_and_b32 s0, s0, -8
	v_writelane_b32 v251, s2, 14
	s_sub_i32 s0, s9, s0
	s_mov_b64 s[56:57], 0x120000
	v_writelane_b32 v251, s3, 15
	s_lshl_b32 s2, s0, 5
	s_cmp_lt_i32 s0, 0
	s_movk_i32 s3, 0x121
	s_cselect_b32 s3, s3, 0x120
	s_mul_i32 s3, s3, s0
	s_mul_i32 s0, s0, 33
	s_cselect_b32 s4, s0, s2
	s_add_i32 s3, s3, s1
	s_mul_hi_i32 s0, s3, 0x38e38e39
	s_lshr_b32 s2, s0, 31
	s_ashr_i32 s0, s0, 5
	s_add_i32 s0, s0, s2
	s_mul_i32 s2, s0, 0x90
	s_sub_i32 s2, s3, s2
	s_bfe_u32 s3, s2, 0x2001d
;     DI bool next(int i, Unit& u) const {
;         const long L = (long)i * G + c; if (L >= nwg) return false;
;         int wgid = (int)L; { const int q = nwg / NXCD, r = nwg % NXCD, xcd = wgid % NXCD, off = wgid / NXCD; wgid = (xcd < r ? xcd * (q + 1) : r * (q + 1) + (xcd - r) * q) + off; }
;         const int nig = WGM * nN, gid = wgid / nig, fm = gid * WGM, gsz = (nM - fm) < WGM ? (nM - fm) : WGM;
;         u.pm = fm + ((wgid % nig) % gsz); u.pn = (wgid % nig) / gsz; return true;
;     }
; DI void tables_stage2(const Params& p, int seg, LAS float* mtab, int bid) {
;     ...
;     const bool narrow = (gridDim.x == 256);
;     const int t_lo = narrow ? 4 * (bid >> 6) + wave : wave, t_hi = narrow ? (wave < 4 ? t_lo + 1 : 0) : NB * 4;
;     const bool pub = narrow ? ((bid & 63) == 0) : (bid == 0);
; DI void phase_ps(const Params& p, int seg, LAS unsigned char* lds, int G, int bid) {
;     ...
;     int item = bid;
;     if (item < NITEM) PS_LOAD(item);
	s_add_i32 s3, s2, s3
	s_and_b32 s5, s3, 0xfffc
	s_sub_i32 s2, s2, s5
	s_lshl_b32 s0, s0, 2
	s_sext_i32_i16 s2, s2
	s_add_i32 s6, s0, s2
	s_sext_i32_i16 s0, s3
	s_ashr_i32 s2, s0, 2
	s_lshr_b32 s0, s0, 2
	s_ashr_i32 s35, s94, 31
	v_writelane_b32 v251, s2, 16
	s_add_u32 s2, s92, 0x480000
	s_addc_u32 s3, s93, 0
	v_writelane_b32 v251, s2, 17
	s_mov_b64 s[14:15], 0x80
	s_mov_b64 s[54:55], 0x400
	v_writelane_b32 v251, s3, 18
	s_add_u32 s2, s92, 0x141000
	s_addc_u32 s3, s93, 0
	v_writelane_b32 v251, s2, 19
	s_nop 1
	v_writelane_b32 v251, s3, 20
	s_ashr_i32 s2, s53, 4
	s_and_b32 s5, s2, -4
	s_and_b64 s[2:3], s[12:13], exec
	s_cselect_b32 s2, s5, 0
	s_and_b32 s5, s53, 63
	v_writelane_b32 v251, s2, 21
	s_and_b64 s[2:3], s[12:13], exec
	s_cselect_b32 s2, s5, s53
	s_cmp_eq_u32 s2, 0
	s_cselect_b64 s[2:3], -1, 0
	v_writelane_b32 v251, s2, 22
	s_nop 1
	v_writelane_b32 v251, s3, 23
	s_add_u32 s2, s92, 0x8000000
	s_addc_u32 s3, s93, 0
	v_writelane_b32 v251, s2, 24
	s_nop 1
	v_writelane_b32 v251, s3, 25
	s_add_u32 s2, s92, 0x121000
	s_addc_u32 s3, s93, 0
	v_writelane_b32 v251, s2, 26
	s_lshl_b32 s78, s94, 9
	s_nop 0
	v_writelane_b32 v251, s3, 27
	s_lshl_b32 s2, s53, 9
	v_writelane_b32 v251, s2, 28
	s_add_u32 s2, s92, 0x580000
	s_addc_u32 s3, s93, 0
	v_writelane_b32 v251, s2, 29
	s_cmpk_lt_i32 s53, 0x800
	s_nop 0
	v_writelane_b32 v251, s3, 30
	s_cselect_b64 s[2:3], -1, 0
	v_writelane_b32 v251, s2, 31
	s_nop 1
	v_writelane_b32 v251, s3, 32
	s_ashr_i32 s2, s53, 31
	s_lshr_b32 s2, s2, 26
	s_add_i32 s2, s53, s2
	s_ashr_i32 s3, s2, 6
	s_and_b32 s2, s2, 0x3ffffc0
	s_sub_i32 s2, s53, s2
	s_cmp_gt_u32 s3, 15
	s_cselect_b64 s[12:13], -1, 0
	s_lshl_b32 s5, s3, 9
	v_writelane_b32 v251, s12, 33
	s_and_b32 s5, s5, 0x600
	s_add_u32 s5, s92, s5
	v_writelane_b32 v251, s13, 34
	v_writelane_b32 v251, s5, 35
	s_addc_u32 s5, s93, 0
	s_lshl_b32 s3, s3, 10
	s_and_b32 s3, s3, 0x3000
	s_lshl_b32 s2, s2, 6
	v_writelane_b32 v251, s5, 36
	s_add_i32 s2, s3, s2
	v_writelane_b32 v251, s2, 37
	s_add_u32 s2, s92, 0x500000
	s_addc_u32 s3, s93, 0
	v_readfirstlane_b32 s5, v1
	v_writelane_b32 v251, s2, 38
	s_cmpk_lt_i32 s5, 0x100
	v_lshrrev_b32_e32 v1, 20, v0
	v_writelane_b32 v251, s3, 39
	s_cselect_b64 s[2:3], -1, 0
	v_writelane_b32 v251, s2, 40
	v_lshrrev_b32_e32 v0, 10, v0
	v_or_b32_e32 v0, v0, v1
	v_writelane_b32 v251, s3, 41
	s_add_u32 s2, s92, 0x1e000000
	s_addc_u32 s3, s93, 0
	v_writelane_b32 v251, s2, 42
	v_and_or_b32 v0, v0, s79, v202
	v_mov_b32_e32 v1, 0
	v_writelane_b32 v251, s3, 43
	s_add_u32 s2, s92, 0x3400000
	v_writelane_b32 v251, s2, 44
	s_addc_u32 s2, s93, 0
	s_cmpk_lt_i32 s9, 0x100
	v_writelane_b32 v251, s2, 45
	s_cselect_b64 s[2:3], -1, 0
	v_writelane_b32 v251, s2, 46
	s_mov_b64 s[12:13], 0
	s_nop 0
	v_writelane_b32 v251, s3, 47
	s_add_u32 s2, s92, 0x10e000
	v_writelane_b32 v251, s2, 48
	s_addc_u32 s2, s93, 0
	v_writelane_b32 v251, s2, 49
	s_add_u32 s2, s92, 0x600000
	v_writelane_b32 v251, s2, 50
	s_addc_u32 s2, s93, 0
	v_writelane_b32 v251, s2, 51
	s_add_u32 s2, s92, 0x4000
	v_writelane_b32 v251, s2, 52
	s_addc_u32 s2, s93, 0
	v_writelane_b32 v251, s2, 53
	s_bfe_i32 s2, s6, 0x10017
	s_lshr_b32 s2, s2, 20
	s_lshl_b32 s3, s6, 8
	s_add_i32 s2, s3, s2
	s_and_b32 s2, s2, 0xfffff000
	s_sub_i32 s2, s3, s2
	s_ashr_i32 s3, s6, 31
	s_lshr_b32 s3, s3, 28
	s_add_i32 s3, s6, s3
	s_lshl_b32 s3, s3, 9
	s_and_b32 s3, s3, 0xffffe000
	v_writelane_b32 v251, s6, 54
	s_add_i32 s2, s2, s3
	s_add_i32 s1, s4, s1
	v_writelane_b32 v251, s2, 55
	s_ashr_i32 s2, s1, 31
	s_lshr_b32 s2, s2, 28
	s_add_i32 s2, s1, s2
	s_and_b32 s3, s2, 0xfff0
	s_sub_i32 s1, s1, s3
	s_bfe_i32 s3, s1, 0x80000
	s_bfe_u32 s3, s3, 0x2000d
	s_add_i32 s3, s1, s3
	s_and_b32 s4, s3, 0xfc
	s_sub_i32 s1, s1, s4
	s_ashr_i32 s2, s2, 4
	s_lshl_b32 s2, s2, 2
	s_sext_i32_i8 s1, s1
	s_add_i32 s4, s2, s1
	s_bfe_i64 s[0:1], s[0:1], 0x100000
	s_lshl_b64 s[0:1], s[0:1], 19
	v_writelane_b32 v251, s0, 56
	s_mov_b32 s6, 1
	s_nop 0
	v_writelane_b32 v251, s1, 57
	s_bfe_i32 s0, s3, 0x80000
	s_sext_i32_i16 s0, s0
	s_lshl_b32 s1, s4, 8
	s_mul_hi_i32 s2, s1, 0x4800
	s_ashr_i32 s1, s0, 2
	s_lshr_b32 s0, s0, 2
	v_writelane_b32 v251, s1, 58
	s_bfe_i64 s[0:1], s[0:1], 0x100000
	s_lshl_b64 s[0:1], s[0:1], 20
	v_writelane_b32 v251, s0, 59
	s_nop 1
	v_writelane_b32 v251, s1, 60
	s_mul_i32 s0, s4, 0x480000
	s_add_u32 s0, s24, s0
	s_addc_u32 s1, s25, s2
	v_writelane_b32 v251, s4, 61
	s_add_u32 s2, s0, 0x240000
	v_writelane_b32 v251, s0, 62
	s_addc_u32 s3, s1, 0
	v_writelane_b32 v250, s2, 0
	v_writelane_b32 v251, s1, 63
	s_mov_b32 s0, s8
	v_writelane_b32 v250, s3, 1
	v_writelane_b32 v250, s0, 2
	s_ashr_i32 s11, s10, 31
	s_lshl_b32 s83, s94, 12
	v_writelane_b32 v250, s1, 3
	s_add_i32 s0, s8, s10
	v_writelane_b32 v250, s0, 4
	s_lshl_b32 s0, s53, 12
	v_writelane_b32 v250, s0, 5
	s_lshl_b32 s0, s53, 6
	v_writelane_b32 v250, s0, 6
	v_writelane_b32 v250, s5, 7
	s_lshl_b32 s0, s5, 3
	v_writelane_b32 v250, s0, 8
	s_add_i32 s0, 0, 0x23ff0
	v_writelane_b32 v250, s0, 9
	s_add_i32 s0, 0, 0x23ff4
	v_writelane_b32 v250, s0, 10
	s_add_i32 s0, 0, 0x16b00
	v_writelane_b32 v250, s0, 11
	s_add_i32 s0, 0, 0x18700
	v_writelane_b32 v250, s0, 12
	v_cmp_eq_u32_e64 s[0:1], 0, v0
	s_add_i32 s36, 0, 0x18c00
	s_mov_b64 s[2:3], -1
	v_writelane_b32 v250, s0, 13
	s_nop 1
	v_writelane_b32 v250, s1, 14
	s_lshl_b64 s[0:1], s[10:11], 5
	v_writelane_b32 v250, s0, 15
	s_nop 1
	v_writelane_b32 v250, s1, 16
	s_lshl_b64 s[0:1], s[10:11], 11
	v_writelane_b32 v250, s0, 17
	s_nop 1
	v_writelane_b32 v250, s1, 18
	s_lshl_b64 s[0:1], s[10:11], 12
	v_writelane_b32 v250, s0, 19
	s_nop 1
	v_writelane_b32 v250, s1, 20
	v_writelane_b32 v250, s97, 21
	v_writelane_b32 v250, s35, 22
	v_writelane_b32 v250, s78, 23
	v_writelane_b32 v250, s83, 24
	s_branch .LBB0_120

; DI void phase_mixer(const Params& p, int seg, LAS unsigned char* lds, int G, int bid) {
;     ...
;         u32x4 pq[4], pk[4], pv; u32x2 pin[2]; float pden = 0.f, pcm = 0.f, pbc = 0.f, pmch = 0.f;
;         const unsigned voq = (unsigned)(((tid >> 5) * qpitch + (tid & 31) * 8) * 2);
;         const unsigned vov = (unsigned)(((tid >> 2) * NPC + (tid & 3) * 8) * 2);
;         const unsigned vop = (unsigned)(((16 * ((tid >> 6) & 3) + (tid & 15)) * NPC + 4 * ((tid & 63) >> 4)) * 2);
;         const size_t qstep16 = (size_t)16 * qpitch * 2;
;     ...
;                 s16x4 t0[4], t1r[4], tv[12];
;                 int lnB = lane;
;                 const int j16 = lnB & 15, h4 = lnB >> 4;
;                 const unsigned addr0 = ldsb + L_KI + (8 * h4 + (j16 >> 2)) * QP + (2 * wave) * 32 + 8 * (lnB & 3);
;                 const unsigned addrv = ldsb + L_VI + (8 * h4 + (j16 >> 2)) * VP2 + 8 * (lnB & 3);
.LBB0_569:
.LBB0_570:
	v_readlane_b32 s0, v252, 4
	v_readlane_b32 s1, v252, 5
	s_cmp_ge_i32 s70, s0
	s_cselect_b64 s[0:1], -1, 0
	s_cmp_lt_i32 s70, s33
	s_cselect_b64 s[8:9], -1, 0
	s_and_b64 s[0:1], s[0:1], s[8:9]
	s_andn2_b64 vcc, exec, s[0:1]
	v_readlane_b32 s0, v250, 58
	s_add_i32 s88, s0, 5
	s_cbranch_vccnz .LBB0_692
	v_mov_b32_e32 v136, v202
	v_readlane_b32 s0, v251, 40
	v_readlane_b32 s1, v251, 41
	v_ashrrev_i32_e32 v0, 6, v136
	s_andn2_b64 vcc, exec, s[0:1]
	v_readfirstlane_b32 s11, v0
	s_cbranch_vccnz .LBB0_624
	s_waitcnt vmcnt(0)
	v_lshlrev_b32_e32 v2, 2, v136
	v_readlane_b32 s0, v251, 42
	v_ashrrev_i32_e32 v3, 31, v2
	v_readlane_b32 s1, v251, 43
	s_lshl_b32 s6, s11, 6
	s_add_i32 s8, 0, 0x11000
	v_lshl_add_u64 v[138:139], v[2:3], 2, s[0:1]
	s_movk_i32 s0, 0x200
	v_and_b32_e32 v2, 15, v136
	v_bfe_u32 v3, v136, 4, 2
	v_ashrrev_i32_e32 v8, 2, v136
	v_lshlrev_b32_e32 v9, 4, v136
	v_lshlrev_b32_e32 v0, 4, v0
	s_and_b32 s9, s11, 3
	v_cmp_gt_i32_e64 s[40:41], s0, v136
	v_lshlrev_b32_e32 v5, 3, v3
	s_add_i32 s0, s8, s6
	v_and_b32_e32 v10, 48, v9
	v_mul_lo_u32 v11, v8, s96
	v_and_or_b32 v159, v0, 48, v2
	s_and_b32 s17, s11, -4
	v_and_b32_e32 v4, 63, v136
	v_add_u32_e32 v6, s0, v5
	v_or_b32_e32 v140, v10, v11
	v_mul_u32_u24_e32 v11, 0x2400, v159
	v_lshlrev_b32_e32 v0, 2, v3
	s_movk_i32 s0, 0x100
	s_cmp_lt_u32 s11, 4
	s_mov_b32 s18, 0x19e00
	v_max_i32_e32 v13, 0, v136
	v_or_b32_e32 v3, v11, v0
	v_cmp_gt_i32_e64 s[42:43], s0, v136
	v_cmp_gt_u32_e64 s[44:45], 16, v4
	v_lshl_or_b32 v161, s9, 4, v2
	s_cselect_b64 s[0:1], -1, 0
	s_cmp_eq_u32 s17, 4
	v_lshl_add_u32 v219, v4, 2, s18
	v_bfe_u32 v4, v136, 2, 2
	v_sub_u32_e32 v13, v13, v136
	v_lshlrev_b32_e32 v7, 3, v136
	v_lshlrev_b32_e32 v142, 1, v3
	v_and_b32_e32 v3, 0x1f0, v9
	v_mul_u32_u24_e32 v9, 0x220, v161
	v_and_b32_e32 v12, 48, v136
	s_cselect_b64 s[70:71], -1, 0
	s_mov_b32 s22, 0x17600
	v_bfe_u32 v4, v136, 2, 4
	s_add_i32 s18, s6, 0
	v_add_u32_e32 v13, 0x1ff, v13
	v_and_b32_e32 v147, 0xf8, v7
	v_add3_u32 v163, 0, v9, v12
	v_add_u32_e32 v218, s22, v10
	v_mul_lo_u32 v220, v8, s37
	v_mul_u32_u24_e32 v8, 0x220, v4
	v_and_b32_e32 v7, 24, v7
	s_add_i32 s19, s18, 0x8800
	v_mul_u32_u24_e32 v4, 0xa0, v4
	v_add_u32_e32 v137, 0x200, v136
	v_add_u32_e32 v9, 0x400, v136
	v_add_u32_e32 v10, 0x600, v136
	v_lshrrev_b32_e32 v14, 9, v13
	v_ashrrev_i32_e32 v145, 5, v136
	v_add3_u32 v221, s19, v7, v8
	v_add3_u32 v222, v7, s22, v4
	v_and_b32_e32 v4, 7, v136
	v_mul_u32_u24_e32 v2, 0x220, v2
	v_ashrrev_i32_e32 v8, 5, v137
	v_ashrrev_i32_e32 v9, 5, v9
	v_ashrrev_i32_e32 v10, 5, v10
	s_add_i32 s18, s18, 0x11020
	v_add_u32_e32 v14, 1, v14
	v_mov_b32_e32 v141, v1
	v_add_u32_e32 v3, 0, v3
	v_cmp_eq_u32_e32 vcc, 0, v4
	v_mul_u32_u24_e32 v7, 0x220, v145
	v_mul_u32_u24_e32 v8, 0x220, v8
	v_mul_u32_u24_e32 v9, 0x220, v9
	v_mul_u32_u24_e32 v10, 0x220, v10
	s_or_b32 s97, s6, 0xc0
	v_add3_u32 v224, s8, v12, v2
	v_add_u32_e32 v12, s18, v5
	s_movk_i32 s6, 0x1ff
	v_and_b32_e32 v225, 0xfffffe, v14
	v_lshl_add_u32 v144, v4, 2, s22
	v_lshrrev_b32_e32 v4, 1, v136
	v_readlane_b32 s8, v250, 7
	v_mov_b32_e32 v143, v1
	v_cndmask_b32_e32 v223, 0, v214, vcc
	s_lshl_b32 s89, s17, 6
	s_mulk_i32 s9, 0xc00
	s_mulk_i32 s11, 0xc00
	v_cmp_lt_u32_e64 s[46:47], s6, v13
	v_lshl_add_u32 v226, v225, 9, v136
	v_cmp_ne_u32_e64 s[48:49], v14, v225
	v_and_b32_e32 v146, 24, v4
	v_or_b32_e32 v227, 64, v159
	v_lshl_add_u64 v[148:149], v[140:141], 0, s[56:57]
	v_lshl_or_b32 v150, v11, 1, v5
	v_mov_b32_e32 v151, v1
	v_lshlrev_b32_e32 v152, 1, v0
	v_add_u32_e32 v228, v6, v2
	v_add_u32_e32 v229, v3, v7
	v_add_u32_e32 v230, v3, v8
	v_add_u32_e32 v231, v3, v9
	v_add_u32_e32 v232, v3, v10
	v_add_u32_e32 v233, v12, v2
	v_readlane_b32 s38, v250, 8
	s_mov_b32 s39, s8
	s_branch .LBB0_574

; DI void phase_mixer(const Params& p, int seg, LAS unsigned char* lds, int G, int bid) {
;     ...
;                 s16x4 t0[4], t1r[4], tv[12];
;                 int lnB = lane;
;                 const int j16 = lnB & 15, h4 = lnB >> 4;
;                 const unsigned addr0 = ldsb + L_KI + (8 * h4 + (j16 >> 2)) * QP + (2 * wave) * 32 + 8 * (lnB & 3);
;                 const unsigned addrv = ldsb + L_VI + (8 * h4 + (j16 >> 2)) * VP2 + 8 * (lnB & 3);
;                 asm volatile("ds_read_b64_tr_b16 %0, %8\n\tds_read_b64_tr_b16 %1, %8 offset:2112\n\tds_read_b64_tr_b16 %2, %8 offset:16896\n\tds_read_b64_tr_b16 %3, %8 offset:19008\n\t"
;                              "ds_read_b64_tr_b16 %4, %8 offset:32\n\tds_read_b64_tr_b16 %5, %8 offset:2144\n\tds_read_b64_tr_b16 %6, %8 offset:16928\n\tds_read_b64_tr_b16 %7, %8 offset:19040\n\ts_waitcnt lgkmcnt(0)"
;                              : "=&v"(t0[0]), "=&v"(t0[1]), "=&v"(t0[2]), "=&v"(t0[3]), "=&v"(t1r[0]), "=&v"(t1r[1]), "=&v"(t1r[2]), "=&v"(t1r[3]) : "v"(addr0) : "memory");
;                 asm volatile("ds_read_b64_tr_b16 %0, %12\n\tds_read_b64_tr_b16 %1, %12 offset:448\n\tds_read_b64_tr_b16 %2, %12 offset:3584\n\tds_read_b64_tr_b16 %3, %12 offset:4032\n\t"
;                              "ds_read_b64_tr_b16 %4, %12 offset:32\n\tds_read_b64_tr_b16 %5, %12 offset:480\n\tds_read_b64_tr_b16 %6, %12 offset:3616\n\tds_read_b64_tr_b16 %7, %12 offset:4064\n\t"
;                              "ds_read_b64_tr_b16 %8, %12 offset:64\n\tds_read_b64_tr_b16 %9, %12 offset:512\n\tds_read_b64_tr_b16 %10, %12 offset:3648\n\tds_read_b64_tr_b16 %11, %12 offset:4096\n\ts_waitcnt lgkmcnt(0)"
;                              : "=&v"(tv[0]), "=&v"(tv[1]), "=&v"(tv[2]), "=&v"(tv[3]), "=&v"(tv[4]), "=&v"(tv[5]), "=&v"(tv[6]), "=&v"(tv[7]), "=&v"(tv[8]), "=&v"(tv[9]), "=&v"(tv[10]), "=&v"(tv[11]) : "v"(addrv) : "memory");
;                 __builtin_amdgcn_sched_barrier(0);
; #pragma unroll
;                 for (int v = 0; v < 3; ++v) if (v < nvt) {
;                     const bf16x8 vb0 = __builtin_shufflevector(tv[4 * v], tv[4 * v + 1], 0, 1, 2, 3, 4, 5, 6, 7);
;                     C[0][v] = __builtin_amdgcn_mfma_f32_16x16x32_bf16(__builtin_shufflevector(t0[0], t0[1], 0, 1, 2, 3, 4, 5, 6, 7), vb0, C[0][v], 0, 0, 0);
.LBB0_610:
	ds_read_b64_tr_b16 v[76:77], v221
	ds_read_b64_tr_b16 v[78:79], v221 offset:8704
	ds_read_b64_tr_b16 v[68:69], v221 offset:17408
	ds_read_b64_tr_b16 v[70:71], v221 offset:26112
	ds_read_b64_tr_b16 v[72:73], v221 offset:32
	ds_read_b64_tr_b16 v[74:75], v221 offset:8736
	ds_read_b64_tr_b16 v[64:65], v221 offset:17440
	ds_read_b64_tr_b16 v[66:67], v221 offset:26144
	s_waitcnt lgkmcnt(0)
	ds_read_b64_tr_b16 v[100:101], v222
	ds_read_b64_tr_b16 v[102:103], v222 offset:2560
	ds_read_b64_tr_b16 v[88:89], v222 offset:5120
	ds_read_b64_tr_b16 v[90:91], v222 offset:7680
	ds_read_b64_tr_b16 v[96:97], v222 offset:32
	ds_read_b64_tr_b16 v[98:99], v222 offset:2592
	ds_read_b64_tr_b16 v[84:85], v222 offset:5152
	ds_read_b64_tr_b16 v[86:87], v222 offset:7712
	s_waitcnt lgkmcnt(0)
	s_nop 0
	v_mfma_f32_16x16x32_bf16 v[12:15], v[76:79], v[100:103], v[12:15]
	s_and_b64 vcc, exec, s[42:43]
	s_cbranch_vccnz .Lmx_wm1
	s_waitcnt vmcnt(6)
	s_branch .Lmx_wm2

; DI void phase_mixer(const Params& p, int seg, LAS unsigned char* lds, int G, int bid) {
;     ...
;                 for (int v = 0; v < 3; ++v) if (v < nvt) {
;                     const bf16x8 vb0 = __builtin_shufflevector(tv[4 * v], tv[4 * v + 1], 0, 1, 2, 3, 4, 5, 6, 7);
;                     C[0][v] = __builtin_amdgcn_mfma_f32_16x16x32_bf16(__builtin_shufflevector(t0[0], t0[1], 0, 1, 2, 3, 4, 5, 6, 7), vb0, C[0][v], 0, 0, 0);
;                     C[1][v] = __builtin_amdgcn_mfma_f32_16x16x32_bf16(__builtin_shufflevector(t1r[0], t1r[1], 0, 1, 2, 3, 4, 5, 6, 7), vb0, C[1][v], 0, 0, 0); }
; #pragma unroll
;                 for (int v = 0; v < 3; ++v) if (v < nvt) {
;                     const bf16x8 vb1 = __builtin_shufflevector(tv[4 * v + 2], tv[4 * v + 3], 0, 1, 2, 3, 4, 5, 6, 7);
;                     C[0][v] = __builtin_amdgcn_mfma_f32_16x16x32_bf16(__builtin_shufflevector(t0[2], t0[3], 0, 1, 2, 3, 4, 5, 6, 7), vb1, C[0][v], 0, 0, 0);
;                     C[1][v] = __builtin_amdgcn_mfma_f32_16x16x32_bf16(__builtin_shufflevector(t1r[2], t1r[3], 0, 1, 2, 3, 4, 5, 6, 7), vb1, C[1][v], 0, 0, 0); }
;             }
; #pragma unroll
;             for (int a = 0; a < 2; ++a)
; #pragma unroll
;                 for (int v = 0; v < 3; ++v) C[a][v] = C[a][v] * g_c;
;             MX_WRITE_CIMG(1.0f);
.Lmx_wm2:
	v_max_f32_e32 v0, v234, v234
	s_add_u32 s35, s35, 64
	s_addc_u32 s22, s22, 0
	v_mfma_f32_16x16x32_bf16 v[8:11], v[76:79], v[96:99], v[8:11]
	s_add_i32 s23, s23, -1
	s_mov_b64 s[18:19], 0x1000
	v_lshl_add_u64 v[172:173], v[172:173], 0, s[54:55]
	v_lshl_add_u64 v[174:175], v[174:175], 0, s[56:57]
	v_lshl_add_u64 v[176:177], v[176:177], 0, s[18:19]
	v_lshl_add_u64 v[178:179], v[178:179], 0, s[54:55]
	v_mfma_f32_16x16x32_bf16 v[20:23], v[72:75], v[100:103], v[20:23]
	v_lshl_add_u64 v[182:183], v[182:183], 0, s[56:57]
	v_lshl_add_u64 v[180:181], v[180:181], 0, s[56:57]
	v_lshl_add_u64 v[184:185], v[184:185], 0, s[26:27]
	v_mfma_f32_16x16x32_bf16 v[28:31], v[72:75], v[96:99], v[28:31]
	v_lshl_add_u64 v[186:187], v[186:187], 0, s[26:27]
	v_lshl_add_u64 v[188:189], v[188:189], 0, s[26:27]
	v_lshl_add_u64 v[190:191], v[190:191], 0, s[26:27]
	v_mfma_f32_16x16x32_bf16 v[12:15], v[68:71], v[88:91], v[12:15]
	v_lshl_add_u64 v[192:193], v[192:193], 0, s[26:27]
	v_lshl_add_u64 v[194:195], v[194:195], 0, s[26:27]
	v_lshl_add_u64 v[196:197], v[196:197], 0, s[26:27]
	s_nop 4
	v_pk_mul_f32 v[14:15], v[158:159], v[14:15] op_sel_hi:[0,1]
	v_pk_mul_f32 v[12:13], v[158:159], v[12:13] op_sel_hi:[0,1]
	v_mfma_f32_16x16x32_bf16 v[8:11], v[68:71], v[84:87], v[8:11]
	v_cvt_pk_bf16_f32 v2, v12, v13
	v_cvt_pk_bf16_f32 v3, v14, v15
	ds_write_b64 v228, v[2:3]
	v_lshl_add_u64 v[198:199], v[198:199], 0, s[26:27]
	s_nop 3
	v_pk_mul_f32 v[10:11], v[158:159], v[10:11] op_sel_hi:[0,1]
	v_pk_mul_f32 v[8:9], v[158:159], v[8:9] op_sel_hi:[0,1]
	v_mfma_f32_16x16x32_bf16 v[20:23], v[64:67], v[88:91], v[20:23]
	v_cvt_pk_bf16_f32 v2, v8, v9
	v_mfma_f32_16x16x32_bf16 v[28:31], v[64:67], v[84:87], v[28:31]
	v_cvt_pk_bf16_f32 v3, v10, v11
	s_nop 4
	v_pk_mul_f32 v[22:23], v[158:159], v[22:23] op_sel_hi:[0,1]
	v_pk_mul_f32 v[20:21], v[158:159], v[20:21] op_sel_hi:[0,1]
	ds_write_b64 v228, v[2:3] offset:8704
	v_pk_mul_f32 v[30:31], v[158:159], v[30:31] op_sel_hi:[0,1]
	v_pk_mul_f32 v[28:29], v[158:159], v[28:29] op_sel_hi:[0,1]
	v_cvt_pk_bf16_f32 v2, v20, v21
	v_cvt_pk_bf16_f32 v3, v22, v23
	ds_write_b64 v233, v[2:3]
	v_cvt_pk_bf16_f32 v2, v28, v29
	v_cvt_pk_bf16_f32 v3, v30, v31
	ds_write_b64 v233, v[2:3] offset:8704
	s_cmp_lg_u32 s32, 0
	s_cbranch_scc0 .Lmxb_noown
	ds_read_b64_tr_b16 v[92:93], v222 offset:64
	ds_read_b64_tr_b16 v[94:95], v222 offset:2624
	ds_read_b64_tr_b16 v[80:81], v222 offset:5184
	ds_read_b64_tr_b16 v[82:83], v222 offset:7744
	s_waitcnt lgkmcnt(0)
	v_mfma_f32_16x16x32_bf16 v[16:19], v[76:79], v[92:95], v[16:19]
	v_mfma_f32_16x16x32_bf16 v[24:27], v[72:75], v[92:95], v[24:27]
	v_mfma_f32_16x16x32_bf16 v[16:19], v[68:71], v[80:83], v[16:19]
	v_mfma_f32_16x16x32_bf16 v[24:27], v[64:67], v[80:83], v[24:27]
	s_nop 7
	s_nop 3
	v_pk_mul_f32 v[18:19], v[158:159], v[18:19] op_sel_hi:[0,1]
	v_pk_mul_f32 v[16:17], v[158:159], v[16:17] op_sel_hi:[0,1]
	v_pk_mul_f32 v[26:27], v[158:159], v[26:27] op_sel_hi:[0,1]
	v_pk_mul_f32 v[24:25], v[158:159], v[24:25] op_sel_hi:[0,1]
	v_cvt_pk_bf16_f32 v2, v16, v17
	v_cvt_pk_bf16_f32 v3, v18, v19
	ds_write_b64 v228, v[2:3] offset:17408
	v_cvt_pk_bf16_f32 v2, v24, v25
	v_cvt_pk_bf16_f32 v3, v26, v27
	ds_write_b64 v233, v[2:3] offset:17408
